# N2 step: scalar next-step selection and tile addresses computed one step ahead behind the K-fragment LDS reads
# baseline (speedup 1.0000x reference)
; __device__ void phaseN2_task(const Params& p, int task, char* lds, bf16_t* ydst, int ystride, volatile unsigned* uex, char* ldsb) {
;     ...
;     {
;         const int lo = (t0 & ~31) - 511;
;         const int jb0 = lo > 0 ? (lo >> 6) : 0;
;         const int kkey = t512 >> 3, kch = (t512 & 7) * 8;
;         const int vd = t512 >> 3, vch = (t512 & 7) * 8;
;         const bf16_t* vtb = (const bf16_t*)(p.ws + OFF_VT) + ((size_t)(b * 2 + g) * 64 + vd) * SEQ + vch;
;         u32x4 kreg, vreg;
;         int br = 0, j = 0;
;         {
;             const bf16_t* kb = Z + (rowb + 0) * ZC + ZKS + g * 64;
;             kreg = *(const u32x4*)(kb + (size_t)kkey * ZC + kch);
;             vreg = *(const u32x4*)(vtb);
;         }
;         f32x4 O[2][4];
;         float m[2] = {-1e30f, -1e30f}, l[2] = {0.f, 0.f};
; #pragma unroll
;         for (int x = 0; x < 2; x++)
; #pragma unroll
;             for (int dt = 0; dt < 4; dt++) O[x][dt] = (f32x4){0.f, 0.f, 0.f, 0.f};
;         for (;;) {
;             __syncthreads();
;             *(u32x4*)(Ks + kkey * 64 + (((kch >> 3) ^ (kkey & 7)) * 8)) = kreg;
;             *(u32x4*)(VT + vd * 72 + vch) = vreg;
;             __syncthreads();
;             int nbr, nj;
;             if (br == 0) {
;                 const unsigned rem = (j >= 31) ? 0u : (uni & ~((2u << j) - 1u));
;                 if (rem) { nbr = 0; nj = __ffs((int)rem) - 1; } else { nbr = 1; nj = jb0; }
;             } else {
;                 if (j < cur) { nbr = 1; nj = j + 1; } else { nbr = 2; nj = 0; }
;             }
;             if (nbr < 2) {
;                 const bf16_t* kb = Z + (rowb + nj * 64) * ZC + (nbr ? ZKW : ZKS) + g * 64;
;                 kreg = *(const u32x4*)(kb + (size_t)kkey * ZC + kch);
;                 vreg = *(const u32x4*)(vtb + (size_t)nbr * (8 * 2 * 64) * SEQ + nj * 64);
;             }
.LBB0_616:
	s_or_b64 exec, exec, s[4:5]
	s_lshl_b32 s4, 2, s76
	s_add_i32 s4, s4, -1
	s_cmp_lg_u32 s76, 31
	s_cselect_b32 s10, s4, -2
	s_add_i32 s4, s1, 0xfffffe01
	s_ashr_i32 s11, s4, 6
	s_lshl_b32 s0, s0, 18
	s_add_u32 s4, s92, s0
	v_ashrrev_i32_e32 v49, 31, v48
	s_addc_u32 s5, s93, 0
	s_mul_i32 s0, s88, 0x2700
	v_lshlrev_b64 v[16:17], 12, v[48:49]
	s_add_u32 s0, s90, s0
	v_lshlrev_b32_e32 v25, 3, v124
	v_lshl_add_u64 v[16:17], s[4:5], 0, v[16:17]
	s_addc_u32 s5, s91, 0
	s_lshl_b32 s12, s89, 6
	s_lshl_b32 s4, s89, 7
	v_and_b32_e32 v34, 56, v25
	s_add_u32 s4, s0, s4
	s_movk_i32 s0, 0x1380
	v_lshlrev_b32_e32 v88, 1, v34
	s_addc_u32 s5, s5, 0
	v_mad_i64_i32 v[94:95], s[6:7], v48, s0, 0
	v_lshl_add_u64 v[36:37], v[16:17], 0, v[88:89]
	v_lshl_add_u64 v[16:17], v[94:95], 1, s[4:5]
	v_lshl_add_u64 v[16:17], v[16:17], 0, v[88:89]
	s_movk_i32 s0, 0x2000
	v_add_co_u32_e32 v16, vcc, s0, v16
	s_mov_b32 s0, 0xf800000
	s_nop 0
	v_addc_co_u32_e32 v17, vcc, 0, v17, vcc
	v_mov_b32_e32 v93, v91
	v_add_co_u32_e32 v20, vcc, s0, v36
	s_waitcnt lgkmcnt(0)
	s_barrier
	flat_load_dword v33, v[90:91] sc0 sc1
	s_waitcnt vmcnt(0)
	flat_load_dword v35, v[92:93] sc0 sc1
	s_waitcnt vmcnt(0)
	v_addc_co_u32_e32 v21, vcc, 0, v37, vcc
	global_load_dwordx4 v[16:19], v[16:17], off offset:512
	s_nop 0
	global_load_dwordx4 v[20:23], v[20:21], off
	v_and_b32_e32 v26, 7, v124
	v_lshlrev_b32_e32 v38, 7, v48
	v_bitop3_b32 v27, v75, v124, 7 bitop3:0x78
	v_bitop3_b32 v40, v25, 56, v124 bitop3:0x48
	v_bitop3_b32 v42, v75, v26, 4 bitop3:0x36
	v_lshlrev_b32_e32 v39, 4, v48
	v_lshlrev_b32_e32 v28, 4, v74
	v_lshlrev_b32_e32 v29, 1, v129
	v_mov_b32_e32 v24, 0
	v_lshlrev_b32_e32 v41, 4, v27
	v_lshl_or_b32 v136, v40, 1, v38
	v_lshlrev_b32_e32 v40, 4, v42
	s_mov_b64 s[4:5], 0xf800000
	s_cmpk_gt_i32 s1, 0x1ff
	s_mov_b32 s89, s85
	v_lshrrev_b32_e32 v93, 16, v127
	v_lshrrev_b32_e32 v133, 16, v128
	v_add_u32_e32 v134, 0xfffffe01, v126
	v_mov_b32_e32 v143, 0
	v_mov_b32_e32 v102, 0xf149f2ca
	s_mov_b64 s[8:9], 0
	v_mov_b32_e32 v103, 0xf149f2ca
	v_mov_b32_e32 v56, 0
	v_add3_u32 v135, v51, v28, v29
	v_mov_b32_e32 v25, v24
	v_mov_b32_e32 v26, v24
	v_mov_b32_e32 v27, v24
	v_mov_b32_e32 v28, v24
	v_mov_b32_e32 v29, v24
	v_mov_b32_e32 v30, v24
	v_mov_b32_e32 v31, v24
	v_mov_b32_e32 v32, v24
	v_lshlrev_b32_e32 v96, 1, v34
	v_add_u32_e32 v137, v51, v41
	v_add3_u32 v138, v38, v39, v88
	v_add_u32_e32 v139, v51, v40
	v_lshl_add_u64 v[98:99], v[36:37], 0, s[4:5]
	s_cselect_b32 s0, s11, 0
	s_lshl_b32 s84, s12, 1
	v_mov_b32_e32 v34, v24
	v_mov_b32_e32 v36, v24
	v_mov_b32_e32 v37, v24
	v_mov_b32_e32 v38, v24
	v_mov_b32_e32 v39, v24
	v_mov_b32_e32 v40, v24
	v_mov_b32_e32 v41, v24
	v_mov_b32_e32 v42, v24
	v_mov_b32_e32 v43, v24
	v_mov_b32_e32 v44, v24
	v_mov_b32_e32 v45, v24
	v_mov_b32_e32 v46, v24
	v_mov_b32_e32 v47, v24
	v_mov_b32_e32 v48, v24
	v_mov_b32_e32 v49, v24
	v_mov_b32_e32 v50, v24
	v_mov_b32_e32 v51, v24
	v_mov_b32_e32 v52, v24
	v_mov_b32_e32 v53, v24
	v_mov_b32_e32 v54, v24
	v_mov_b32_e32 v55, v24
	v_mov_b32_e32 v100, v24
	v_mov_b32_e32 v101, v24
	s_waitcnt lgkmcnt(0)
	v_bitop3_b32 v140, v35, s10, v33 bitop3:0xc8
	v_mov_b32_e32 v33, v24
	v_mov_b32_e32 v35, v24
	v_mov_b32_e32 v176, 0
	v_mov_b32_e32 v177, 0
	v_mov_b32_e32 v178, v123
	v_mov_b32_e32 v179, v123
	s_mov_b32 s34, 0
	s_mov_b32 s35, 0
	v_lshl_add_u32 v183, v94, 1, v96
	v_readfirstlane_b32 s56, v98
	v_readfirstlane_b32 s57, v99
	v_readfirstlane_b32 s54, v140
	s_nop 1
	v_subrev_u32_e32 v163, s56, v98
	v_add_u32_e32 v216, 0x4800, v135
	v_add_u32_e32 v217, 0x5000, v135
	v_add_u32_e32 v218, 0x5800, v135
	v_add_u32_e32 v219, 0x6000, v135
	s_cmp_eq_u32 s34, 0
	s_cbranch_scc0 .Ln2_n_winP
	s_lshl_b32 s65, -2, s35
	s_and_b32 s65, s54, s65
	s_cmp_gt_i32 s35, 30
	s_cselect_b32 s65, 0, s65
	s_ff1_i32_b32 s51, s65
	s_cmp_eq_u32 s65, 0
	s_cselect_b32 s52, 1, 0
	s_cselect_b32 s51, s0, s51
	s_branch .Ln2_n_adrP
.Ln2_n_winP:
	s_add_i32 s51, s35, 1
	s_cmp_lt_i32 s35, s76
	s_cselect_b32 s52, 1, 2
	s_cselect_b32 s51, s51, 0
	s_cmp_eq_u32 s34, 2
	s_cselect_b32 s52, 2, s52
	s_cselect_b32 s51, 0, s51
.Ln2_n_adrP:
	s_lshl_b32 s65, s51, 6
	s_add_i32 s66, s65, s88
	s_mul_i32 s66, s66, s97
	s_movk_i32 s67, 0x2400
	s_cmp_eq_u32 s52, 0
	s_cselect_b32 s67, 0x2200, s67
	s_add_i32 s66, s66, s67
	s_add_i32 s66, s66, s84
	s_add_u32 s58, s90, s66
	s_addc_u32 s59, s91, 0
	s_lshl_b32 s67, s52, 22
	s_lshl_b32 s65, s65, 1
	s_add_i32 s67, s67, s65
	s_add_u32 s60, s56, s67
	s_addc_u32 s61, s57, 0
	s_branch .LBB0_618
.LBB0_617:
	s_or_b64 exec, exec, s[6:7]
	v_cmp_eq_u32_e32 vcc, 2, v141
	s_or_b64 s[8:9], vcc, s[8:9]
	v_mov_b32_e32 v102, v97
	v_mov_b32_e32 v103, v88
	v_mov_b32_e32 v143, v141
	s_mov_b32 s34, s52
	s_mov_b32 s35, s51
	s_mov_b32 s52, s63
	s_mov_b32 s51, s64
	s_andn2_b64 exec, exec, s[8:9]
	s_cbranch_execz .LBB0_593
	.p2alignl 6, 3212836864
.LBB0_618:
	s_cmp_eq_u32 s34, 0
	s_cselect_b64 s[4:5], -1, 0
	s_lshl_b32 s53, s35, 6
	s_sub_i32 s50, 31, s35
	s_barrier
	s_waitcnt vmcnt(1)
	ds_write_b128 v136, v[16:19]
	s_waitcnt vmcnt(0)
	ds_write_b128 v138, v[20:23] offset:18432
	v_mov_b32_e32 v141, s52
	v_mov_b32_e32 v142, s51
	v_subrev_u32_e32 v88, s53, v126
	s_cmp_eq_u32 s34, 0
	s_cbranch_scc1 .Ln2_t_sel
	v_subrev_u32_e32 v97, s53, v134
	v_max_i32_e32 v97, 0, v97
	s_branch .Ln2_t_k

; __device__ __forceinline__ f32x4 mfma16(bf16x8 a, bf16x8 b, f32x4 c) { return __builtin_amdgcn_mfma_f32_16x16x32_bf16(a, b, c, 0, 0, 0); }
; __device__ __forceinline__ void nsa_block_step(const bf16_t* Ks, const bf16_t* VT, const bf16x8 (&qf)[2][2], f32x4 (&O)[2][4], float (&m)[2], float (&l)[2],
;                                                int klo, int khi, int r, int q) {
;     f32x4 s[2][4];
; #pragma unroll
;     for (int x = 0; x < 2; x++)
; #pragma unroll
;         for (int kt = 0; kt < 4; kt++) s[x][kt] = (f32x4){0.f, 0.f, 0.f, 0.f};
; #pragma unroll
;     for (int kt = 0; kt < 4; kt++)
; #pragma unroll
;         for (int ks = 0; ks < 2; ks++) {
;             const bf16x8 kf = ld_frag(Ks + (kt * 16 + r) * 64 + (((ks * 4 + q) ^ (r & 7)) * 8));
; #pragma unroll
;             for (int x = 0; x < 2; x++) s[x][kt] = mfma16(kf, qf[x][ks], s[x][kt]);
;         }
;     if (!__all((klo <= 0) && (khi >= 63))) {
;         const int a = 4 * q - klo;
;         const unsigned range = (unsigned)(khi - klo);
;         const bool any = khi >= klo;
; #pragma unroll
;         for (int kt = 0; kt < 4; kt++)
; #pragma unroll
;             for (int j = 0; j < 4; j++) {
;                 const bool valid = any && ((unsigned)(kt * 16 + j + a) <= range);
; #pragma unroll
;                 for (int x = 0; x < 2; x++) s[x][kt][j] = valid ? s[x][kt][j] : -3.0e38f;
;             }
;     }
; __device__ void phaseN2_task(const Params& p, int task, char* lds, bf16_t* ydst, int ystride, volatile unsigned* uex, char* ldsb) {
;     ...
;             int nbr, nj;
;             if (br == 0) {
;                 const unsigned rem = (j >= 31) ? 0u : (uni & ~((2u << j) - 1u));
;                 if (rem) { nbr = 0; nj = __ffs((int)rem) - 1; } else { nbr = 1; nj = jb0; }
;             } else {
;                 if (j < cur) { nbr = 1; nj = j + 1; } else { nbr = 2; nj = 0; }
;             }
;             if (nbr < 2) {
;                 const bf16_t* kb = Z + (rowb + nj * 64) * ZC + (nbr ? ZKW : ZKS) + g * 64;
;                 kreg = *(const u32x4*)(kb + (size_t)kkey * ZC + kch);
;                 vreg = *(const u32x4*)(vtb + (size_t)nbr * (8 * 2 * 64) * SEQ + nj * 64);
;             }
.Ln2_t_noload:
	s_barrier
	ds_read_b128 v[56:59], v137
	ds_read_b128 v[68:71], v139
	ds_read_b128 v[60:63], v137 offset:2048
	ds_read_b128 v[76:79], v139 offset:2048
	v_cmp_eq_u32_e32 vcc, 0, v97
	v_cmp_lt_i32_e64 s[6:7], 62, v88
	v_cmp_lt_i32_e64 s[48:49], v88, v97
	ds_read_b128 v[240:243], v137 offset:4096
	ds_read_b128 v[104:107], v139 offset:4096
	s_and_b64 s[6:7], vcc, s[6:7]
	s_or_b64 s[46:47], s[6:7], s[48:49]
	s_cmp_eq_u64 s[46:47], exec
	s_cselect_b64 s[48:49], s[48:49], 0
	ds_read_b128 v[244:247], v137 offset:6144
	ds_read_b128 v[108:111], v139 offset:6144
	v_cndmask_b32_e64 v168, v176, v123, s[48:49]
	v_cndmask_b32_e64 v169, v176, v123, s[48:49]
	v_cndmask_b32_e64 v170, v176, v123, s[48:49]
	v_cndmask_b32_e64 v171, v176, v123, s[48:49]
	v_cndmask_b32_e64 v172, v177, v123, s[48:49]
	v_cndmask_b32_e64 v173, v177, v123, s[48:49]
	v_cndmask_b32_e64 v174, v177, v123, s[48:49]
	v_cndmask_b32_e64 v175, v177, v123, s[48:49]
	s_cmp_eq_u32 s52, 0
	s_cbranch_scc0 .Ln2_n_winL
	s_lshl_b32 s65, -2, s51
	s_and_b32 s65, s54, s65
	s_cmp_gt_i32 s51, 30
	s_cselect_b32 s65, 0, s65
	s_ff1_i32_b32 s64, s65
	s_cmp_eq_u32 s65, 0
	s_cselect_b32 s63, 1, 0
	s_cselect_b32 s64, s0, s64
	s_branch .Ln2_n_adrL
.Ln2_n_winL:
	s_add_i32 s64, s51, 1
	s_cmp_lt_i32 s51, s76
	s_cselect_b32 s63, 1, 2
	s_cselect_b32 s64, s64, 0
	s_cmp_eq_u32 s52, 2
	s_cselect_b32 s63, 2, s63
	s_cselect_b32 s64, 0, s64
.Ln2_n_adrL:
	s_lshl_b32 s65, s64, 6
	s_add_i32 s66, s65, s88
	s_mul_i32 s66, s66, s97
	s_movk_i32 s67, 0x2400
	s_cmp_eq_u32 s63, 0
	s_cselect_b32 s67, 0x2200, s67
	s_add_i32 s66, s66, s67
	s_add_i32 s66, s66, s84
	s_add_u32 s58, s90, s66
	s_addc_u32 s59, s91, 0
	s_lshl_b32 s67, s63, 22
	s_lshl_b32 s65, s65, 1
	s_add_i32 s67, s67, s65
	s_add_u32 s60, s56, s67
	s_addc_u32 s61, s57, 0
	s_waitcnt lgkmcnt(7)
	v_mfma_f32_16x16x32_bf16 v[64:67], v[56:59], v[0:3], v[168:171]
	v_mfma_f32_16x16x32_bf16 v[56:59], v[56:59], v[8:11], v[172:175]
	s_waitcnt lgkmcnt(6)
	v_mfma_f32_16x16x32_bf16 v[80:83], v[68:71], v[4:7], v[64:67]
	v_mfma_f32_16x16x32_bf16 v[68:71], v[68:71], v[12:15], v[56:59]
	s_waitcnt lgkmcnt(5)
	v_mfma_f32_16x16x32_bf16 v[56:59], v[60:63], v[0:3], v[168:171]
	v_mfma_f32_16x16x32_bf16 v[60:63], v[60:63], v[8:11], v[172:175]
	s_waitcnt lgkmcnt(4)
	v_mfma_f32_16x16x32_bf16 v[72:75], v[76:79], v[4:7], v[56:59]
	v_mfma_f32_16x16x32_bf16 v[64:67], v[76:79], v[12:15], v[60:63]
	s_waitcnt lgkmcnt(3)
	v_mfma_f32_16x16x32_bf16 v[60:63], v[240:243], v[0:3], v[168:171]
	v_mfma_f32_16x16x32_bf16 v[56:59], v[240:243], v[8:11], v[172:175]
	s_waitcnt lgkmcnt(2)
	v_mfma_f32_16x16x32_bf16 v[84:87], v[104:107], v[4:7], v[60:63]
	v_mfma_f32_16x16x32_bf16 v[60:63], v[104:107], v[12:15], v[56:59]
	s_waitcnt lgkmcnt(1)
	v_mfma_f32_16x16x32_bf16 v[56:59], v[244:247], v[0:3], v[168:171]
	v_mfma_f32_16x16x32_bf16 v[104:107], v[244:247], v[8:11], v[172:175]
	s_waitcnt lgkmcnt(0)
	v_mfma_f32_16x16x32_bf16 v[76:79], v[108:111], v[4:7], v[56:59]
	v_mfma_f32_16x16x32_bf16 v[56:59], v[108:111], v[12:15], v[104:107]
	s_cmp_eq_u64 s[46:47], exec
	s_cbranch_scc1 .LBB0_628
	s_nop 1
	v_min_i32_e32 v88, 63, v88
	v_sub_u32_e32 v104, v88, v97
	v_cmp_ge_i32_e32 vcc, v88, v97
	v_sub_u32_e32 v88, v129, v97
	v_cmp_le_u32_e64 s[6:7], v88, v104
	s_and_b64 s[6:7], vcc, s[6:7]
	v_add_u32_e32 v97, 1, v88
	v_cndmask_b32_e64 v80, v123, v80, s[6:7]
	v_cndmask_b32_e64 v68, v123, v68, s[6:7]
	v_cmp_le_u32_e64 s[6:7], v97, v104
	s_and_b64 s[6:7], vcc, s[6:7]
	v_add_u32_e32 v97, 2, v88
	v_cndmask_b32_e64 v81, v123, v81, s[6:7]
	v_cndmask_b32_e64 v69, v123, v69, s[6:7]
	v_cmp_le_u32_e64 s[6:7], v97, v104
	s_and_b64 s[6:7], vcc, s[6:7]
	v_add_u32_e32 v97, 3, v88
	v_cndmask_b32_e64 v82, v123, v82, s[6:7]
	v_cndmask_b32_e64 v70, v123, v70, s[6:7]
	v_cmp_le_u32_e64 s[6:7], v97, v104
	s_and_b64 s[6:7], vcc, s[6:7]
	v_add_u32_e32 v97, 16, v88
	v_cndmask_b32_e64 v83, v123, v83, s[6:7]
	v_cndmask_b32_e64 v71, v123, v71, s[6:7]
	v_cmp_le_u32_e64 s[6:7], v97, v104
	s_and_b64 s[6:7], vcc, s[6:7]
	v_add_u32_e32 v97, 17, v88
	v_cndmask_b32_e64 v72, v123, v72, s[6:7]
	v_cndmask_b32_e64 v64, v123, v64, s[6:7]
	v_cmp_le_u32_e64 s[6:7], v97, v104
	s_and_b64 s[6:7], vcc, s[6:7]
	v_add_u32_e32 v97, 18, v88
	v_cndmask_b32_e64 v73, v123, v73, s[6:7]
	v_cndmask_b32_e64 v65, v123, v65, s[6:7]
	v_cmp_le_u32_e64 s[6:7], v97, v104
	s_and_b64 s[6:7], vcc, s[6:7]
	v_add_u32_e32 v97, 19, v88
	v_cndmask_b32_e64 v74, v123, v74, s[6:7]
	v_cndmask_b32_e64 v66, v123, v66, s[6:7]
	v_cmp_le_u32_e64 s[6:7], v97, v104
	s_and_b64 s[6:7], vcc, s[6:7]
	v_add_u32_e32 v97, 32, v88
	v_cndmask_b32_e64 v75, v123, v75, s[6:7]
	v_cndmask_b32_e64 v67, v123, v67, s[6:7]
	v_cmp_le_u32_e64 s[6:7], v97, v104
	s_and_b64 s[6:7], vcc, s[6:7]
	v_add_u32_e32 v97, 33, v88
	v_cndmask_b32_e64 v84, v123, v84, s[6:7]
	v_cndmask_b32_e64 v60, v123, v60, s[6:7]
	v_cmp_le_u32_e64 s[6:7], v97, v104
	s_and_b64 s[6:7], vcc, s[6:7]
	v_add_u32_e32 v97, 34, v88
	v_cndmask_b32_e64 v85, v123, v85, s[6:7]
	v_cndmask_b32_e64 v61, v123, v61, s[6:7]
	v_cmp_le_u32_e64 s[6:7], v97, v104
	s_and_b64 s[6:7], vcc, s[6:7]
	v_add_u32_e32 v97, 35, v88
	v_cndmask_b32_e64 v86, v123, v86, s[6:7]
	v_cndmask_b32_e64 v62, v123, v62, s[6:7]
	v_cmp_le_u32_e64 s[6:7], v97, v104
	s_and_b64 s[6:7], vcc, s[6:7]
	v_add_u32_e32 v97, 48, v88
	v_cndmask_b32_e64 v87, v123, v87, s[6:7]
	v_cndmask_b32_e64 v63, v123, v63, s[6:7]
	v_cmp_le_u32_e64 s[6:7], v97, v104
	s_and_b64 s[6:7], vcc, s[6:7]
	v_add_u32_e32 v97, 49, v88
	v_cndmask_b32_e64 v76, v123, v76, s[6:7]
	v_cndmask_b32_e64 v56, v123, v56, s[6:7]
	v_cmp_le_u32_e64 s[6:7], v97, v104
	s_and_b64 s[6:7], vcc, s[6:7]
	v_add_u32_e32 v97, 50, v88
	v_cndmask_b32_e64 v77, v123, v77, s[6:7]
	v_cndmask_b32_e64 v57, v123, v57, s[6:7]
	v_cmp_le_u32_e64 s[6:7], v97, v104
	s_and_b64 s[6:7], vcc, s[6:7]
	v_add_u32_e32 v88, 51, v88
	v_cndmask_b32_e64 v78, v123, v78, s[6:7]
	v_cndmask_b32_e64 v58, v123, v58, s[6:7]
	v_cmp_le_u32_e64 s[6:7], v88, v104
	s_and_b64 vcc, vcc, s[6:7]
	v_cndmask_b32_e32 v79, v123, v79, vcc
	v_cndmask_b32_e32 v59, v123, v59, vcc

; __device__ __forceinline__ float exp2f_(float x) { return __builtin_amdgcn_exp2f(x); }
; __device__ __forceinline__ f32x4 mfma16(bf16x8 a, bf16x8 b, f32x4 c) { return __builtin_amdgcn_mfma_f32_16x16x32_bf16(a, b, c, 0, 0, 0); }
; __device__ __forceinline__ void nsa_block_step(const bf16_t* Ks, const bf16_t* VT, const bf16x8 (&qf)[2][2], f32x4 (&O)[2][4], float (&m)[2], float (&l)[2],
;                                                int klo, int khi, int r, int q) {
;     ...
;     bf16x8 pbv[2][2];
; #pragma unroll
;     for (int x = 0; x < 2; x++) {
;         float mx = fmaxf(fmaxf(fmaxf(s[x][0][0], s[x][0][1]), fmaxf(s[x][0][2], s[x][0][3])), fmaxf(fmaxf(s[x][1][0], s[x][1][1]), fmaxf(s[x][1][2], s[x][1][3])));
;         mx = fmaxf(mx, fmaxf(fmaxf(fmaxf(s[x][2][0], s[x][2][1]), fmaxf(s[x][2][2], s[x][2][3])), fmaxf(fmaxf(s[x][3][0], s[x][3][1]), fmaxf(s[x][3][2], s[x][3][3]))));
;         mx = xrow_max(mx);
;         const float mnew = fmaxf(m[x], mx);
;         const float alpha = exp2f_(m[x] - mnew);
;         m[x] = mnew;
;         float ls = 0.f;
; #pragma unroll
;         for (int kt = 0; kt < 4; kt++)
; #pragma unroll
;             for (int j = 0; j < 4; j++) { const float pv = exp2f_(s[x][kt][j] - mnew); s[x][kt][j] = pv; ls += pv; }
;         l[x] = l[x] * alpha + ls;
; #pragma unroll
;         for (int dt = 0; dt < 4; dt++) O[x][dt] *= alpha;
; #pragma unroll
;         for (int s2 = 0; s2 < 2; s2++) {
;             const u32x4 t4 = {pack2(s[x][2 * s2][0], s[x][2 * s2][1]), pack2(s[x][2 * s2][2], s[x][2 * s2][3]),
;                               pack2(s[x][2 * s2 + 1][0], s[x][2 * s2 + 1][1]), pack2(s[x][2 * s2 + 1][2], s[x][2 * s2 + 1][3])};
;             pbv[x][s2] = __builtin_bit_cast(bf16x8, t4);
;         }
;     }
; #pragma unroll
;     for (int s2 = 0; s2 < 2; s2++)
; #pragma unroll
;         for (int dt = 0; dt < 4; dt++) {
;             const u32x2 lo = *(const u32x2*)(VT + (dt * 16 + r) * 72 + (2 * s2) * 16 + 4 * q);
;             const u32x2 hi = *(const u32x2*)(VT + (dt * 16 + r) * 72 + (2 * s2 + 1) * 16 + 4 * q);
;             const bf16x8 va = mk_frag(lo, hi);
; #pragma unroll
;             for (int x = 0; x < 2; x++) O[x][dt] = mfma16(va, pbv[x][s2], O[x][dt]);
;         }
.Ln2_fast:
	ds_read2_b64 v[200:203], v216 offset1:4
	ds_read2_b64 v[204:207], v217 offset0:32 offset1:36
	ds_read2_b64 v[208:211], v218 offset0:64 offset1:68
	ds_read2_b64 v[212:215], v219 offset0:96 offset1:100
	v_exp_f32_e32 v80, v80
	v_exp_f32_e32 v81, v81
	v_exp_f32_e32 v82, v82
	v_exp_f32_e32 v83, v83
	v_exp_f32_e32 v72, v72
	v_exp_f32_e32 v73, v73
	v_exp_f32_e32 v74, v74
	v_exp_f32_e32 v75, v75
	ds_read2_b64 v[224:227], v216 offset0:8 offset1:12
	ds_read2_b64 v[228:231], v217 offset0:40 offset1:44
	v_exp_f32_e32 v68, v68
	v_exp_f32_e32 v69, v69
	v_exp_f32_e32 v70, v70
	v_exp_f32_e32 v71, v71
	v_exp_f32_e32 v64, v64
	v_exp_f32_e32 v65, v65
	v_exp_f32_e32 v66, v66
	v_exp_f32_e32 v67, v67
	ds_read2_b64 v[232:235], v218 offset0:72 offset1:76
	ds_read2_b64 v[236:239], v219 offset0:104 offset1:108
	v_cvt_pk_bf16_f32 v184, v80, v81
	v_cvt_pk_bf16_f32 v185, v82, v83
	v_cvt_pk_bf16_f32 v186, v72, v73
	v_cvt_pk_bf16_f32 v187, v74, v75
	v_cvt_pk_bf16_f32 v192, v68, v69
	v_cvt_pk_bf16_f32 v193, v70, v71
	v_cvt_pk_bf16_f32 v194, v64, v65
	v_cvt_pk_bf16_f32 v195, v66, v67
	v_exp_f32_e32 v84, v84
	v_exp_f32_e32 v85, v85
	s_waitcnt lgkmcnt(7)
	v_mfma_f32_16x16x32_bf16 v[52:55], v[200:203], v[184:187], v[52:55]
	v_exp_f32_e32 v86, v86
	v_exp_f32_e32 v87, v87
	v_mfma_f32_16x16x32_bf16 v[36:39], v[200:203], v[192:195], v[36:39]
	v_exp_f32_e32 v76, v76
	v_exp_f32_e32 v77, v77
	s_waitcnt lgkmcnt(6)
	v_mfma_f32_16x16x32_bf16 v[48:51], v[204:207], v[184:187], v[48:51]
	v_exp_f32_e32 v78, v78
	v_exp_f32_e32 v79, v79
	v_mfma_f32_16x16x32_bf16 v[32:35], v[204:207], v[192:195], v[32:35]
	v_exp_f32_e32 v60, v60
	v_exp_f32_e32 v61, v61
	s_waitcnt lgkmcnt(5)
	v_mfma_f32_16x16x32_bf16 v[44:47], v[208:211], v[184:187], v[44:47]
	v_exp_f32_e32 v62, v62
	v_exp_f32_e32 v63, v63
	v_mfma_f32_16x16x32_bf16 v[28:31], v[208:211], v[192:195], v[28:31]
	v_exp_f32_e32 v56, v56
	v_exp_f32_e32 v57, v57
	s_waitcnt lgkmcnt(4)
	v_mfma_f32_16x16x32_bf16 v[40:43], v[212:215], v[184:187], v[40:43]
	v_exp_f32_e32 v58, v58
	v_exp_f32_e32 v59, v59
	v_mfma_f32_16x16x32_bf16 v[24:27], v[212:215], v[192:195], v[24:27]
	v_cvt_pk_bf16_f32 v188, v84, v85
	v_cvt_pk_bf16_f32 v189, v86, v87
	v_cvt_pk_bf16_f32 v190, v76, v77
	v_cvt_pk_bf16_f32 v191, v78, v79
	v_cvt_pk_bf16_f32 v196, v60, v61
	v_cvt_pk_bf16_f32 v197, v62, v63
	v_cvt_pk_bf16_f32 v198, v56, v57
	v_cvt_pk_bf16_f32 v199, v58, v59
	v_add_f32_e32 v221, v80, v81
	v_add_f32_e32 v220, v68, v69
	s_waitcnt lgkmcnt(3)
	v_mfma_f32_16x16x32_bf16 v[52:55], v[224:227], v[188:191], v[52:55]
	v_add_f32_e32 v221, v221, v82
	v_add_f32_e32 v220, v220, v70
	v_mfma_f32_16x16x32_bf16 v[36:39], v[224:227], v[196:199], v[36:39]
	v_add_f32_e32 v221, v221, v83
	v_add_f32_e32 v220, v220, v71
	s_waitcnt lgkmcnt(2)
	v_mfma_f32_16x16x32_bf16 v[48:51], v[228:231], v[188:191], v[48:51]
	v_add_f32_e32 v221, v221, v72
	v_add_f32_e32 v220, v220, v64
	v_mfma_f32_16x16x32_bf16 v[32:35], v[228:231], v[196:199], v[32:35]
	v_add_f32_e32 v221, v221, v73
	v_add_f32_e32 v220, v220, v65
	s_waitcnt lgkmcnt(1)
	v_mfma_f32_16x16x32_bf16 v[44:47], v[232:235], v[188:191], v[44:47]
	v_add_f32_e32 v221, v221, v74
	v_add_f32_e32 v220, v220, v66
	v_mfma_f32_16x16x32_bf16 v[28:31], v[232:235], v[196:199], v[28:31]
	v_add_f32_e32 v221, v221, v75
	v_add_f32_e32 v220, v220, v67
	s_waitcnt lgkmcnt(0)
	v_mfma_f32_16x16x32_bf16 v[40:43], v[236:239], v[188:191], v[40:43]
	v_add_f32_e32 v221, v221, v84
	v_add_f32_e32 v220, v220, v60
	v_mfma_f32_16x16x32_bf16 v[24:27], v[236:239], v[196:199], v[24:27]
	v_add_f32_e32 v221, v221, v85
	v_add_f32_e32 v220, v220, v61
	v_add_f32_e32 v221, v221, v86
	v_add_f32_e32 v220, v220, v62
	v_add_f32_e32 v221, v221, v87
	v_add_f32_e32 v220, v220, v63
	v_add_f32_e32 v221, v221, v76
	v_add_f32_e32 v220, v220, v56
	v_add_f32_e32 v221, v221, v77
	v_add_f32_e32 v220, v220, v57
	v_add_f32_e32 v221, v221, v78
	v_add_f32_e32 v220, v220, v58
	v_add_f32_e32 v221, v221, v79
	v_add_f32_e32 v220, v220, v59
	v_cmp_ne_u32_e32 vcc, v141, v143
	v_mov_b32_e32 v88, v103
	v_mov_b32_e32 v97, v102
	v_pk_add_f32 v[100:101], v[100:101], v[220:221]
	s_branch .Ln2_tail
